# stack: tile-head prefetch of G1 row partials (v14) + 4 redundant lgkmcnt waits removed in GEMM loop (v16) + K_VT epilogue 16 partial loads issued at once with counted waits
# baseline (speedup 1.0000x reference)
; #define PG8_STAGE(bufoff, gbase, voff) do { _Pragma("unroll") for (int _i = 0; _i < 2; ++_i) \
;         __builtin_amdgcn_global_load_lds((const unsigned*)((const char*)(gbase) + (voff)[_i]), (LAS unsigned*)(lds + (bufoff) + ldsw + _i * 8192), 16, 0, 0); } while (0)
; #define PG8_LDA(dst, b, h) do { _Pragma("unroll") for (int m = 0; m < 4; ++m) _Pragma("unroll") for (int k = 0; k < 2; ++k) dst[m][k] = *(const LAS bf16x8*)(lds + PG8_SA(b, h) + aoff + m * 2048 + k * 1024); } while (0)
; #define PG8_LDB(dst, b, h) do { _Pragma("unroll") for (int n = 0; n < 2; ++n) _Pragma("unroll") for (int k = 0; k < 2; ++k) dst[n][k] = *(const LAS bf16x8*)(lds + PG8_SB(b, h) + boff + n * 2048 + k * 1024); } while (0)
; #define PG8_MMA(ai, bj, At, Bt) do { __builtin_amdgcn_s_setprio(1); _Pragma("unroll") for (int m = 0; m < 4; ++m) _Pragma("unroll") for (int n = 0; n < 2; ++n) _Pragma("unroll") for (int k = 0; k < 2; ++k) \
;         acc[ai][bj][m][n] = __builtin_amdgcn_mfma_f32_16x16x32_bf16(Bt[n][k], At[m][k], acc[ai][bj][m][n], 0, 0, 0); __builtin_amdgcn_s_setprio(0); } while (0)
; #define PG8_WAIT_V(n) asm volatile("s_waitcnt vmcnt(" #n ")" ::: "memory")
; #define PG8_WAIT_L(n) asm volatile("s_waitcnt lgkmcnt(" #n ")" ::: "memory")
; #define PG8_BAR __builtin_amdgcn_s_barrier()
; #define PG8_SCHED __builtin_amdgcn_sched_barrier(0)
; template <class EpiT>
; __device__ __forceinline__ void gemm_phase(LAS unsigned char* lds, const Gemm g, const StaticOrder& S, const EpiT& E, int wv) {
;     ...
;         for (int t = 0; t < nt; t += 2) {
;             const bool last = (t == nt - 2);
;             const char* a1 = cA + (size_t)(t + 1) * kstep;
;             const char* a2 = last ? nA : cA + (size_t)(t + 2) * kstep; const char* b2 = last ? nB : cB + (size_t)(t + 2) * kstep;
;             const char* a3 = a2 + kstep; const char* b3 = b2 + kstep;
;             PG8_LDB(B0, 0, 0); PG8_LDB(B1, 0, 1); PG8_SCHED; PG8_LDA(At, 0, 0); PG8_STAGE(PG8_SA(1, 1), a1 + hA, voffA);
;             PG8_WAIT_V(8); PG8_WAIT_L(0); PG8_BAR; PG8_MMA(0, 0, At, B0); PG8_MMA(0, 1, At, B1); PG8_BAR; PG8_SCHED;
;             PG8_LDA(At, 0, 1); PG8_STAGE(PG8_SB(0, 0), b2, voffB); PG8_STAGE(PG8_SB(0, 1), b2 + hB, voffB); PG8_STAGE(PG8_SA(0, 0), a2, voffA);
;             PG8_WAIT_V(8); PG8_WAIT_L(0); PG8_BAR; PG8_MMA(1, 0, At, B0); PG8_MMA(1, 1, At, B1); PG8_BAR; PG8_SCHED;
.Lg1rd_skipA:
.LBB0_271:
	s_add_i32 s42, s22, 2
	s_add_u32 s43, s0, 0x80
	s_addc_u32 s23, s1, 0
	s_add_i32 s64, 0, 0x10000
	s_cmp_eq_u32 s52, s22
	s_cselect_b32 s23, s19, s23
	s_cselect_b32 s22, s18, s43
	v_add_u32_e32 v0, s64, v234
	s_cselect_b32 s45, s21, s41
	s_cselect_b32 s44, s20, s40
	s_add_i32 s43, 0, 0x14000
	ds_read_b128 v[134:137], v0
	ds_read_b128 v[138:141], v0 offset:1024
	ds_read_b128 v[142:145], v0 offset:2048
	ds_read_b128 v[146:149], v0 offset:3072
	v_add_u32_e32 v0, s43, v234
	ds_read_b128 v[150:153], v0
	ds_read_b128 v[154:157], v0 offset:1024
	ds_read_b128 v[158:161], v0 offset:2048
	ds_read_b128 v[162:165], v0 offset:3072
	s_add_i32 m0, s14, 0xc000
	ds_read_b128 v[166:169], v242
	ds_read_b128 v[170:173], v242 offset:1024
	ds_read_b128 v[174:177], v242 offset:2048
	ds_read_b128 v[178:181], v242 offset:3072
	ds_read_b128 v[204:207], v242 offset:4096
	ds_read_b128 v[208:211], v242 offset:5120
	ds_read_b128 v[212:215], v242 offset:6144
	ds_read_b128 v[216:219], v242 offset:7168
	global_load_lds_dwordx4 v196, s[0:1]
	s_add_i32 m0, s14, 0xe000
	s_nop 0
	global_load_lds_dwordx4 v198, s[0:1]
	s_waitcnt vmcnt(8)
	s_waitcnt lgkmcnt(0)
	s_barrier
	s_setprio 1
	v_mfma_f32_16x16x32_bf16 v[130:133], v[134:137], v[166:169], v[130:133]
	v_mfma_f32_16x16x32_bf16 v[126:129], v[142:145], v[166:169], v[126:129]
	v_mfma_f32_16x16x32_bf16 v[114:117], v[134:137], v[174:177], v[114:117]
	v_mfma_f32_16x16x32_bf16 v[110:113], v[142:145], v[174:177], v[110:113]
	v_mfma_f32_16x16x32_bf16 v[98:101], v[134:137], v[204:207], v[98:101]
	v_mfma_f32_16x16x32_bf16 v[94:97], v[142:145], v[204:207], v[94:97]
	v_mfma_f32_16x16x32_bf16 v[82:85], v[134:137], v[212:215], v[82:85]
	v_mfma_f32_16x16x32_bf16 v[78:81], v[142:145], v[212:215], v[78:81]
	v_mfma_f32_16x16x32_bf16 v[130:133], v[138:141], v[170:173], v[130:133]
	v_mfma_f32_16x16x32_bf16 v[126:129], v[146:149], v[170:173], v[126:129]
	v_mfma_f32_16x16x32_bf16 v[114:117], v[138:141], v[178:181], v[114:117]
	v_mfma_f32_16x16x32_bf16 v[110:113], v[146:149], v[178:181], v[110:113]
	v_mfma_f32_16x16x32_bf16 v[98:101], v[138:141], v[208:211], v[98:101]
	v_mfma_f32_16x16x32_bf16 v[94:97], v[146:149], v[208:211], v[94:97]
	v_mfma_f32_16x16x32_bf16 v[82:85], v[138:141], v[216:219], v[82:85]
	v_mfma_f32_16x16x32_bf16 v[78:81], v[146:149], v[216:219], v[78:81]
	s_setprio 0
	s_setprio 1
	v_mfma_f32_16x16x32_bf16 v[122:125], v[150:153], v[166:169], v[122:125]
	v_mfma_f32_16x16x32_bf16 v[118:121], v[158:161], v[166:169], v[118:121]
	v_mfma_f32_16x16x32_bf16 v[106:109], v[150:153], v[174:177], v[106:109]
	v_mfma_f32_16x16x32_bf16 v[102:105], v[158:161], v[174:177], v[102:105]
	v_mfma_f32_16x16x32_bf16 v[90:93], v[150:153], v[204:207], v[90:93]
	v_mfma_f32_16x16x32_bf16 v[86:89], v[158:161], v[204:207], v[86:89]
	v_mfma_f32_16x16x32_bf16 v[74:77], v[150:153], v[212:215], v[74:77]
	v_mfma_f32_16x16x32_bf16 v[70:73], v[158:161], v[212:215], v[70:73]
	v_mfma_f32_16x16x32_bf16 v[122:125], v[154:157], v[170:173], v[122:125]
	v_mfma_f32_16x16x32_bf16 v[118:121], v[162:165], v[170:173], v[118:121]
	v_mfma_f32_16x16x32_bf16 v[106:109], v[154:157], v[178:181], v[106:109]
	v_mfma_f32_16x16x32_bf16 v[102:105], v[162:165], v[178:181], v[102:105]
	v_mfma_f32_16x16x32_bf16 v[90:93], v[154:157], v[208:211], v[90:93]
	v_mfma_f32_16x16x32_bf16 v[86:89], v[162:165], v[208:211], v[86:89]
	v_mfma_f32_16x16x32_bf16 v[74:77], v[154:157], v[216:219], v[74:77]
	v_mfma_f32_16x16x32_bf16 v[70:73], v[162:165], v[216:219], v[70:73]
	s_setprio 0
	s_barrier
	s_add_i32 s64, s64, s13
	s_mov_b32 m0, s64
	s_add_u32 s36, s44, 0x80
	s_addc_u32 s37, s45, 0
	ds_read_b128 v[166:169], v242 offset:16384
	ds_read_b128 v[170:173], v242 offset:17408
	ds_read_b128 v[174:177], v242 offset:18432
	ds_read_b128 v[178:181], v242 offset:19456
	ds_read_b128 v[204:207], v242 offset:20480
	ds_read_b128 v[208:211], v242 offset:21504
	ds_read_b128 v[212:215], v242 offset:22528
	ds_read_b128 v[216:219], v242 offset:23552
	global_load_lds_dwordx4 v182, s[44:45]
	s_add_i32 m0, s64, 0x2000
	s_add_i32 s43, s43, s13
	global_load_lds_dwordx4 v186, s[44:45]
	s_add_u32 s44, s44, s8
	s_addc_u32 s45, s45, 0
	s_mov_b32 m0, s43
	s_add_u32 s38, s44, 0x80
	s_addc_u32 s39, s45, 0
	global_load_lds_dwordx4 v182, s[44:45]
	s_add_i32 m0, s43, 0x2000
	s_add_u32 s46, s22, 0x80
	s_addc_u32 s47, s23, 0
	global_load_lds_dwordx4 v186, s[44:45]
	s_mov_b32 m0, s14
	s_nop 0
	global_load_lds_dwordx4 v14, s[22:23]
	s_mov_b32 m0, s15
	s_nop 0
	global_load_lds_dwordx4 v184, s[22:23]
	s_waitcnt vmcnt(8)
	s_waitcnt lgkmcnt(0)
	s_barrier
; #define PG8_STAGE(bufoff, gbase, voff) do { _Pragma("unroll") for (int _i = 0; _i < 2; ++_i) \
;         __builtin_amdgcn_global_load_lds((const unsigned*)((const char*)(gbase) + (voff)[_i]), (LAS unsigned*)(lds + (bufoff) + ldsw + _i * 8192), 16, 0, 0); } while (0)
; #define PG8_LDA(dst, b, h) do { _Pragma("unroll") for (int m = 0; m < 4; ++m) _Pragma("unroll") for (int k = 0; k < 2; ++k) dst[m][k] = *(const LAS bf16x8*)(lds + PG8_SA(b, h) + aoff + m * 2048 + k * 1024); } while (0)
; #define PG8_LDB(dst, b, h) do { _Pragma("unroll") for (int n = 0; n < 2; ++n) _Pragma("unroll") for (int k = 0; k < 2; ++k) dst[n][k] = *(const LAS bf16x8*)(lds + PG8_SB(b, h) + boff + n * 2048 + k * 1024); } while (0)
; #define PG8_MMA(ai, bj, At, Bt) do { __builtin_amdgcn_s_setprio(1); _Pragma("unroll") for (int m = 0; m < 4; ++m) _Pragma("unroll") for (int n = 0; n < 2; ++n) _Pragma("unroll") for (int k = 0; k < 2; ++k) \
;         acc[ai][bj][m][n] = __builtin_amdgcn_mfma_f32_16x16x32_bf16(Bt[n][k], At[m][k], acc[ai][bj][m][n], 0, 0, 0); __builtin_amdgcn_s_setprio(0); } while (0)
; #define PG8_WAIT_V(n) asm volatile("s_waitcnt vmcnt(" #n ")" ::: "memory")
; #define PG8_WAIT_L(n) asm volatile("s_waitcnt lgkmcnt(" #n ")" ::: "memory")
; #define PG8_BAR __builtin_amdgcn_s_barrier()
; #define PG8_SCHED __builtin_amdgcn_sched_barrier(0)
; template <class EpiT>
; __device__ __forceinline__ void gemm_phase(LAS unsigned char* lds, const Gemm g, const StaticOrder& S, const EpiT& E, int wv) {
;     ...
;             PG8_WAIT_V(8); PG8_WAIT_L(0); PG8_BAR; PG8_MMA(1, 0, At, B0); PG8_MMA(1, 1, At, B1); PG8_BAR; PG8_SCHED;
;             PG8_LDB(B0, 1, 0); PG8_LDB(B1, 1, 1); PG8_SCHED; PG8_LDA(At, 1, 0); PG8_STAGE(PG8_SA(0, 1), a2 + hA, voffA);
;             PG8_WAIT_V(8); PG8_WAIT_L(0); PG8_BAR; PG8_MMA(0, 0, At, B0); PG8_MMA(0, 1, At, B1); PG8_BAR; PG8_SCHED;
	s_setprio 1
	v_mfma_f32_16x16x32_bf16 v[66:69], v[134:137], v[166:169], v[66:69]
	v_mfma_f32_16x16x32_bf16 v[62:65], v[142:145], v[166:169], v[62:65]
	v_mfma_f32_16x16x32_bf16 v[50:53], v[134:137], v[174:177], v[50:53]
	v_mfma_f32_16x16x32_bf16 v[46:49], v[142:145], v[174:177], v[46:49]
	v_mfma_f32_16x16x32_bf16 v[34:37], v[134:137], v[204:207], v[34:37]
	v_mfma_f32_16x16x32_bf16 v[30:33], v[142:145], v[204:207], v[30:33]
	v_mfma_f32_16x16x32_bf16 v[18:21], v[134:137], v[212:215], v[18:21]
	v_mfma_f32_16x16x32_bf16 v[10:13], v[142:145], v[212:215], v[10:13]
	v_mfma_f32_16x16x32_bf16 v[66:69], v[138:141], v[170:173], v[66:69]
	v_mfma_f32_16x16x32_bf16 v[62:65], v[146:149], v[170:173], v[62:65]
	v_mfma_f32_16x16x32_bf16 v[50:53], v[138:141], v[178:181], v[50:53]
	v_mfma_f32_16x16x32_bf16 v[46:49], v[146:149], v[178:181], v[46:49]
	v_mfma_f32_16x16x32_bf16 v[34:37], v[138:141], v[208:211], v[34:37]
	v_mfma_f32_16x16x32_bf16 v[30:33], v[146:149], v[208:211], v[30:33]
	v_mfma_f32_16x16x32_bf16 v[18:21], v[138:141], v[216:219], v[18:21]
	v_mfma_f32_16x16x32_bf16 v[10:13], v[146:149], v[216:219], v[10:13]
	s_setprio 0
	s_setprio 1
	v_mfma_f32_16x16x32_bf16 v[58:61], v[150:153], v[166:169], v[58:61]
	v_mfma_f32_16x16x32_bf16 v[54:57], v[158:161], v[166:169], v[54:57]
	v_mfma_f32_16x16x32_bf16 v[42:45], v[150:153], v[174:177], v[42:45]
	v_mfma_f32_16x16x32_bf16 v[38:41], v[158:161], v[174:177], v[38:41]
	v_mfma_f32_16x16x32_bf16 v[26:29], v[150:153], v[204:207], v[26:29]
	v_mfma_f32_16x16x32_bf16 v[22:25], v[158:161], v[204:207], v[22:25]
	v_mfma_f32_16x16x32_bf16 v[6:9], v[150:153], v[212:215], v[6:9]
	v_mfma_f32_16x16x32_bf16 v[2:5], v[158:161], v[212:215], v[2:5]
	v_mfma_f32_16x16x32_bf16 v[58:61], v[154:157], v[170:173], v[58:61]
	v_mfma_f32_16x16x32_bf16 v[54:57], v[162:165], v[170:173], v[54:57]
	v_mfma_f32_16x16x32_bf16 v[42:45], v[154:157], v[178:181], v[42:45]
	v_mfma_f32_16x16x32_bf16 v[38:41], v[162:165], v[178:181], v[38:41]
	v_mfma_f32_16x16x32_bf16 v[26:29], v[154:157], v[208:211], v[26:29]
	v_mfma_f32_16x16x32_bf16 v[22:25], v[162:165], v[208:211], v[22:25]
	v_mfma_f32_16x16x32_bf16 v[6:9], v[154:157], v[216:219], v[6:9]
	v_mfma_f32_16x16x32_bf16 v[2:5], v[162:165], v[216:219], v[2:5]
	s_setprio 0
	s_barrier
	s_add_i32 s43, 0, 0x18000
	v_add_u32_e32 v0, s43, v234
	s_add_i32 s44, 0, 0x1c000
	ds_read_b128 v[134:137], v0
	ds_read_b128 v[138:141], v0 offset:1024
	ds_read_b128 v[142:145], v0 offset:2048
	ds_read_b128 v[146:149], v0 offset:3072
	v_add_u32_e32 v0, s44, v234
	ds_read_b128 v[150:153], v0
	ds_read_b128 v[154:157], v0 offset:1024
	ds_read_b128 v[158:161], v0 offset:2048
	ds_read_b128 v[162:165], v0 offset:3072
	s_add_u32 s22, s22, s4
	s_addc_u32 s23, s23, 0
	s_mov_b32 m0, s88
	ds_read_b128 v[166:169], v242 offset:32768
	ds_read_b128 v[170:173], v242 offset:33792
	ds_read_b128 v[174:177], v242 offset:34816
	ds_read_b128 v[178:181], v242 offset:35840
	ds_read_b128 v[204:207], v242 offset:36864
	ds_read_b128 v[208:211], v242 offset:37888
	ds_read_b128 v[212:215], v242 offset:38912
	ds_read_b128 v[216:219], v242 offset:39936
	global_load_lds_dwordx4 v14, s[22:23]
	s_mov_b32 m0, s89
	s_nop 0
	global_load_lds_dwordx4 v184, s[22:23]
	s_waitcnt vmcnt(8)
	s_waitcnt lgkmcnt(0)
	s_barrier
	s_setprio 1
	v_mfma_f32_16x16x32_bf16 v[130:133], v[134:137], v[166:169], v[130:133]
	v_mfma_f32_16x16x32_bf16 v[126:129], v[142:145], v[166:169], v[126:129]
	v_mfma_f32_16x16x32_bf16 v[114:117], v[134:137], v[174:177], v[114:117]
	v_mfma_f32_16x16x32_bf16 v[110:113], v[142:145], v[174:177], v[110:113]
	v_mfma_f32_16x16x32_bf16 v[98:101], v[134:137], v[204:207], v[98:101]
	v_mfma_f32_16x16x32_bf16 v[94:97], v[142:145], v[204:207], v[94:97]
	v_mfma_f32_16x16x32_bf16 v[82:85], v[134:137], v[212:215], v[82:85]
	v_mfma_f32_16x16x32_bf16 v[78:81], v[142:145], v[212:215], v[78:81]
	v_mfma_f32_16x16x32_bf16 v[130:133], v[138:141], v[170:173], v[130:133]
	v_mfma_f32_16x16x32_bf16 v[126:129], v[146:149], v[170:173], v[126:129]
	v_mfma_f32_16x16x32_bf16 v[114:117], v[138:141], v[178:181], v[114:117]
	v_mfma_f32_16x16x32_bf16 v[110:113], v[146:149], v[178:181], v[110:113]
	v_mfma_f32_16x16x32_bf16 v[98:101], v[138:141], v[208:211], v[98:101]
	v_mfma_f32_16x16x32_bf16 v[94:97], v[146:149], v[208:211], v[94:97]
	v_mfma_f32_16x16x32_bf16 v[82:85], v[138:141], v[216:219], v[82:85]
	v_mfma_f32_16x16x32_bf16 v[78:81], v[146:149], v[216:219], v[78:81]
	s_setprio 0
	s_setprio 1
	v_mfma_f32_16x16x32_bf16 v[122:125], v[150:153], v[166:169], v[122:125]
	v_mfma_f32_16x16x32_bf16 v[118:121], v[158:161], v[166:169], v[118:121]
	v_mfma_f32_16x16x32_bf16 v[106:109], v[150:153], v[174:177], v[106:109]
	v_mfma_f32_16x16x32_bf16 v[102:105], v[158:161], v[174:177], v[102:105]
	v_mfma_f32_16x16x32_bf16 v[90:93], v[150:153], v[204:207], v[90:93]
	v_mfma_f32_16x16x32_bf16 v[86:89], v[158:161], v[204:207], v[86:89]
	v_mfma_f32_16x16x32_bf16 v[74:77], v[150:153], v[212:215], v[74:77]
	v_mfma_f32_16x16x32_bf16 v[70:73], v[158:161], v[212:215], v[70:73]
	v_mfma_f32_16x16x32_bf16 v[122:125], v[154:157], v[170:173], v[122:125]
	v_mfma_f32_16x16x32_bf16 v[118:121], v[162:165], v[170:173], v[118:121]
	v_mfma_f32_16x16x32_bf16 v[106:109], v[154:157], v[178:181], v[106:109]
	v_mfma_f32_16x16x32_bf16 v[102:105], v[162:165], v[178:181], v[102:105]
	v_mfma_f32_16x16x32_bf16 v[90:93], v[154:157], v[208:211], v[90:93]
	v_mfma_f32_16x16x32_bf16 v[86:89], v[162:165], v[208:211], v[86:89]
	v_mfma_f32_16x16x32_bf16 v[74:77], v[154:157], v[216:219], v[74:77]
	v_mfma_f32_16x16x32_bf16 v[70:73], v[162:165], v[216:219], v[70:73]
	s_setprio 0
	s_barrier
; #define PG8_STAGE(bufoff, gbase, voff) do { _Pragma("unroll") for (int _i = 0; _i < 2; ++_i) \
;         __builtin_amdgcn_global_load_lds((const unsigned*)((const char*)(gbase) + (voff)[_i]), (LAS unsigned*)(lds + (bufoff) + ldsw + _i * 8192), 16, 0, 0); } while (0)
; #define PG8_LDA(dst, b, h) do { _Pragma("unroll") for (int m = 0; m < 4; ++m) _Pragma("unroll") for (int k = 0; k < 2; ++k) dst[m][k] = *(const LAS bf16x8*)(lds + PG8_SA(b, h) + aoff + m * 2048 + k * 1024); } while (0)
; #define PG8_MMA(ai, bj, At, Bt) do { __builtin_amdgcn_s_setprio(1); _Pragma("unroll") for (int m = 0; m < 4; ++m) _Pragma("unroll") for (int n = 0; n < 2; ++n) _Pragma("unroll") for (int k = 0; k < 2; ++k) \
;         acc[ai][bj][m][n] = __builtin_amdgcn_mfma_f32_16x16x32_bf16(Bt[n][k], At[m][k], acc[ai][bj][m][n], 0, 0, 0); __builtin_amdgcn_s_setprio(0); } while (0)
; #define PG8_WAIT_V(n) asm volatile("s_waitcnt vmcnt(" #n ")" ::: "memory")
; #define PG8_WAIT_L(n) asm volatile("s_waitcnt lgkmcnt(" #n ")" ::: "memory")
; #define PG8_BAR __builtin_amdgcn_s_barrier()
; #define PG8_SCHED __builtin_amdgcn_sched_barrier(0)
; template <class EpiT>
; __device__ __forceinline__ void gemm_phase(LAS unsigned char* lds, const Gemm g, const StaticOrder& S, const EpiT& E, int wv) {
;     ...
;             PG8_LDA(At, 1, 1); PG8_STAGE(PG8_SB(1, 0), b3, voffB); PG8_STAGE(PG8_SB(1, 1), b3 + hB, voffB); PG8_STAGE(PG8_SA(1, 0), a3, voffA);
;             PG8_WAIT_V(8); PG8_WAIT_L(0); PG8_BAR; PG8_MMA(1, 0, At, B0); PG8_MMA(1, 1, At, B1); PG8_BAR; PG8_SCHED;
;         }
	s_add_i32 s22, s43, s13
	s_mov_b32 m0, s22
	ds_read_b128 v[166:169], v242 offset:49152
	ds_read_b128 v[170:173], v242 offset:50176
	ds_read_b128 v[174:177], v242 offset:51200
	ds_read_b128 v[178:181], v242 offset:52224
	ds_read_b128 v[204:207], v242 offset:53248
	ds_read_b128 v[208:211], v242 offset:54272
	ds_read_b128 v[212:215], v242 offset:55296
	ds_read_b128 v[216:219], v242 offset:56320
	global_load_lds_dwordx4 v182, s[36:37]
	s_add_i32 m0, s22, 0x2000
	s_add_i32 s22, s44, s13
	global_load_lds_dwordx4 v186, s[36:37]
	s_mov_b32 m0, s22
	s_nop 0
	global_load_lds_dwordx4 v182, s[38:39]
	s_add_i32 m0, s22, 0x2000
	s_nop 0
	global_load_lds_dwordx4 v186, s[38:39]
	s_mov_b32 m0, s72
	s_nop 0
	global_load_lds_dwordx4 v14, s[46:47]
	s_mov_b32 m0, s73
	s_nop 0
	global_load_lds_dwordx4 v184, s[46:47]
	s_waitcnt vmcnt(8)
	s_waitcnt lgkmcnt(0)
	s_barrier
	s_setprio 1
	v_mfma_f32_16x16x32_bf16 v[66:69], v[134:137], v[166:169], v[66:69]
	v_mfma_f32_16x16x32_bf16 v[62:65], v[142:145], v[166:169], v[62:65]
	v_mfma_f32_16x16x32_bf16 v[50:53], v[134:137], v[174:177], v[50:53]
	v_mfma_f32_16x16x32_bf16 v[46:49], v[142:145], v[174:177], v[46:49]
	v_mfma_f32_16x16x32_bf16 v[34:37], v[134:137], v[204:207], v[34:37]
	v_mfma_f32_16x16x32_bf16 v[30:33], v[142:145], v[204:207], v[30:33]
	v_mfma_f32_16x16x32_bf16 v[18:21], v[134:137], v[212:215], v[18:21]
	v_mfma_f32_16x16x32_bf16 v[10:13], v[142:145], v[212:215], v[10:13]
	v_mfma_f32_16x16x32_bf16 v[66:69], v[138:141], v[170:173], v[66:69]
	v_mfma_f32_16x16x32_bf16 v[62:65], v[146:149], v[170:173], v[62:65]
	v_mfma_f32_16x16x32_bf16 v[50:53], v[138:141], v[178:181], v[50:53]
	v_mfma_f32_16x16x32_bf16 v[46:49], v[146:149], v[178:181], v[46:49]
	v_mfma_f32_16x16x32_bf16 v[34:37], v[138:141], v[208:211], v[34:37]
	v_mfma_f32_16x16x32_bf16 v[30:33], v[146:149], v[208:211], v[30:33]
	v_mfma_f32_16x16x32_bf16 v[18:21], v[138:141], v[216:219], v[18:21]
	v_mfma_f32_16x16x32_bf16 v[10:13], v[146:149], v[216:219], v[10:13]
	s_setprio 0
	s_setprio 1
	v_mfma_f32_16x16x32_bf16 v[58:61], v[150:153], v[166:169], v[58:61]
	v_mfma_f32_16x16x32_bf16 v[54:57], v[158:161], v[166:169], v[54:57]
	v_mfma_f32_16x16x32_bf16 v[42:45], v[150:153], v[174:177], v[42:45]
	v_mfma_f32_16x16x32_bf16 v[38:41], v[158:161], v[174:177], v[38:41]
	v_mfma_f32_16x16x32_bf16 v[26:29], v[150:153], v[204:207], v[26:29]
	v_mfma_f32_16x16x32_bf16 v[22:25], v[158:161], v[204:207], v[22:25]
	v_mfma_f32_16x16x32_bf16 v[6:9], v[150:153], v[212:215], v[6:9]
	v_mfma_f32_16x16x32_bf16 v[2:5], v[158:161], v[212:215], v[2:5]
	v_mfma_f32_16x16x32_bf16 v[58:61], v[154:157], v[170:173], v[58:61]
	v_mfma_f32_16x16x32_bf16 v[54:57], v[162:165], v[170:173], v[54:57]
	v_mfma_f32_16x16x32_bf16 v[42:45], v[154:157], v[178:181], v[42:45]
	v_mfma_f32_16x16x32_bf16 v[38:41], v[162:165], v[178:181], v[38:41]
	v_mfma_f32_16x16x32_bf16 v[26:29], v[154:157], v[208:211], v[26:29]
	v_mfma_f32_16x16x32_bf16 v[22:25], v[162:165], v[208:211], v[22:25]
	v_mfma_f32_16x16x32_bf16 v[6:9], v[154:157], v[216:219], v[6:9]
	v_mfma_f32_16x16x32_bf16 v[2:5], v[162:165], v[216:219], v[2:5]
	s_setprio 0
	s_barrier
	s_add_u32 s0, s0, 0x100
	s_addc_u32 s1, s1, 0
	s_add_u32 s40, s40, 0x100
	s_addc_u32 s41, s41, 0
	s_cmp_ge_i32 s42, s81
	s_mov_b32 s22, s42
	s_cbranch_scc0 .LBB0_271
	s_and_b64 vcc, exec, s[16:17]
	s_cbranch_vccnz .LBB0_278

;     __device__ __forceinline__ void operator()(const f32x4 (&acc)[2][2][4][2], const pg8::Unit& u, int wr, int wc, int fr, int fq) const {
;     ...
;             case K_VT: {
;                 bf16_t* vt = (bf16_t*)(ws + WS_V); const float* ssqkv = (const float*)(ws + WS_SSQKV);
;                 const int c0 = u.pn * pg8::BM + wc * 32 + 8 * fq; float sc[2][8];
; #pragma unroll
;                 for (int hf = 0; hf < 2; ++hf)
; #pragma unroll
;                     for (int i = 0; i < 8; ++i) { const f32x4 pp = *(const f32x4*)(ssqkv + (size_t)(c0 + 128 * hf + i) * 4); sc[hf][i] = __builtin_amdgcn_rsqf(((pp[0] + pp[1]) + (pp[2] + pp[3])) * (1.f / 256.f) + EPS); }
.LBB0_300:
	s_cmp_eq_u32 s35, 6
	s_mov_b64 s[22:23], -1
	s_cbranch_scc0 .LBB0_302
	v_lshl_or_b32 v150, s71, 8, v241
	v_ashrrev_i32_e32 v151, 31, v150
	v_lshl_add_u64 v[146:147], v[150:151], 4, s[58:59]
	global_load_dwordx4 v[134:137], v[146:147], off offset:48
	global_load_dwordx4 v[138:141], v[146:147], off offset:32
	global_load_dwordx4 v[142:145], v[146:147], off offset:16
	s_nop 0
	global_load_dwordx4 v[146:149], v[146:147], off
	v_or_b32_e32 v230, 4, v150
	v_ashrrev_i32_e32 v231, 31, v230
	v_lshl_add_u64 v[230:231], v[230:231], 4, s[58:59]
	global_load_dwordx4 v[166:169], v[230:231], off offset:48
	global_load_dwordx4 v[170:173], v[230:231], off offset:32
	global_load_dwordx4 v[174:177], v[230:231], off offset:16
	global_load_dwordx4 v[178:181], v[230:231], off
	v_or_b32_e32 v230, 0x80, v150
	v_ashrrev_i32_e32 v231, 31, v230
	v_lshl_add_u64 v[230:231], v[230:231], 4, s[58:59]
	global_load_dwordx4 v[204:207], v[230:231], off offset:48
	global_load_dwordx4 v[208:211], v[230:231], off offset:32
	global_load_dwordx4 v[212:215], v[230:231], off offset:16
	global_load_dwordx4 v[216:219], v[230:231], off
	v_or_b32_e32 v230, 0x84, v150
	v_ashrrev_i32_e32 v231, 31, v230
	v_lshl_add_u64 v[230:231], v[230:231], 4, s[58:59]
	global_load_dwordx4 v[220:223], v[230:231], off offset:48
	global_load_dwordx4 v[224:227], v[230:231], off offset:32
	global_load_dwordx4 v[244:247], v[230:231], off offset:16
	global_load_dwordx4 v[248:251], v[230:231], off
	v_readlane_b32 s22, v255, 20
	v_readlane_b32 s23, v255, 21
	s_mov_b32 s36, 0x10400
	s_waitcnt vmcnt(12)
	v_mov_b32_e32 v152, v147
	v_mov_b32_e32 v153, v148
	v_mov_b32_e32 v147, v149
	v_pk_add_f32 v[146:147], v[152:153], v[146:147]
	s_nop 0
	v_add_f32_e32 v0, v146, v147
	v_mov_b32_e32 v146, v143
	v_mov_b32_e32 v147, v144
	v_mov_b32_e32 v143, v145
	v_pk_add_f32 v[142:143], v[146:147], v[142:143]
	v_fmamk_f32 v0, v0, 0x3b800000, v229
	v_add_f32_e32 v142, v142, v143
	v_fmamk_f32 v142, v142, 0x3b800000, v229
	v_rsq_f32_e32 v152, v142
	v_mov_b32_e32 v142, v139
	v_mov_b32_e32 v143, v140
	v_mov_b32_e32 v139, v141
	v_pk_add_f32 v[138:139], v[142:143], v[138:139]
	v_rsq_f32_e32 v0, v0
	v_add_f32_e32 v138, v138, v139
	v_fmamk_f32 v138, v138, 0x3b800000, v229
	v_rsq_f32_e32 v153, v138
	v_mov_b32_e32 v138, v135
	v_mov_b32_e32 v139, v136
	v_mov_b32_e32 v135, v137
	v_pk_add_f32 v[134:135], v[138:139], v[134:135]
	s_nop 0
	v_add_f32_e32 v134, v134, v135
	v_fmamk_f32 v134, v134, 0x3b800000, v229
	v_rsq_f32_e32 v154, v134
	s_waitcnt vmcnt(8)
	v_mov_b32_e32 v134, v166
	v_mov_b32_e32 v135, v167
	v_mov_b32_e32 v136, v168
	v_mov_b32_e32 v137, v169
	v_mov_b32_e32 v138, v170
	v_mov_b32_e32 v139, v171
	v_mov_b32_e32 v140, v172
	v_mov_b32_e32 v141, v173
	v_mov_b32_e32 v142, v174
	v_mov_b32_e32 v143, v175
	v_mov_b32_e32 v144, v176
	v_mov_b32_e32 v145, v177
	v_mov_b32_e32 v146, v178
	v_mov_b32_e32 v147, v179
	v_mov_b32_e32 v148, v180
	v_mov_b32_e32 v149, v181
	v_mov_b32_e32 v156, v147
	v_mov_b32_e32 v157, v148
	v_mov_b32_e32 v147, v149
	v_pk_add_f32 v[146:147], v[156:157], v[146:147]
	s_nop 0
	v_add_f32_e32 v146, v146, v147
	v_fmamk_f32 v146, v146, 0x3b800000, v229
	v_rsq_f32_e32 v155, v146
	v_mov_b32_e32 v146, v143
	v_mov_b32_e32 v147, v144
	v_mov_b32_e32 v143, v145
	v_pk_add_f32 v[142:143], v[146:147], v[142:143]
	s_nop 0
	v_add_f32_e32 v142, v142, v143
	v_fmamk_f32 v142, v142, 0x3b800000, v229
	v_rsq_f32_e32 v156, v142
	v_mov_b32_e32 v142, v139
	v_mov_b32_e32 v143, v140
	v_mov_b32_e32 v139, v141
	v_pk_add_f32 v[138:139], v[142:143], v[138:139]
	s_nop 0
	v_add_f32_e32 v138, v138, v139
	v_fmamk_f32 v138, v138, 0x3b800000, v229
	v_rsq_f32_e32 v157, v138
	v_mov_b32_e32 v138, v135
	v_mov_b32_e32 v139, v136
	v_mov_b32_e32 v135, v137
	v_pk_add_f32 v[134:135], v[138:139], v[134:135]
	s_nop 0
	v_add_f32_e32 v134, v134, v135
	v_fmamk_f32 v134, v134, 0x3b800000, v229
	v_rsq_f32_e32 v158, v134
	s_waitcnt vmcnt(4)
	v_mov_b32_e32 v134, v204
	v_mov_b32_e32 v135, v205
	v_mov_b32_e32 v136, v206
	v_mov_b32_e32 v137, v207
	v_mov_b32_e32 v138, v208
	v_mov_b32_e32 v139, v209
	v_mov_b32_e32 v140, v210
	v_mov_b32_e32 v141, v211
	v_mov_b32_e32 v142, v212
	v_mov_b32_e32 v143, v213
	v_mov_b32_e32 v144, v214
	v_mov_b32_e32 v145, v215
	v_mov_b32_e32 v146, v216
	v_mov_b32_e32 v147, v217
	v_mov_b32_e32 v148, v218
	v_mov_b32_e32 v149, v219
	v_mov_b32_e32 v160, v147
	v_mov_b32_e32 v161, v148
	v_mov_b32_e32 v147, v149
	v_pk_add_f32 v[146:147], v[160:161], v[146:147]
	s_nop 0
	v_add_f32_e32 v146, v146, v147
	v_fmamk_f32 v146, v146, 0x3b800000, v229
	v_rsq_f32_e32 v159, v146
	v_mov_b32_e32 v146, v143
	v_mov_b32_e32 v147, v144
	v_mov_b32_e32 v143, v145
	v_pk_add_f32 v[142:143], v[146:147], v[142:143]
	s_nop 0
	v_add_f32_e32 v142, v142, v143
	v_fmamk_f32 v142, v142, 0x3b800000, v229
	v_rsq_f32_e32 v160, v142
	v_mov_b32_e32 v142, v139
	v_mov_b32_e32 v143, v140
	v_mov_b32_e32 v139, v141
	v_pk_add_f32 v[138:139], v[142:143], v[138:139]
	s_nop 0
	v_add_f32_e32 v138, v138, v139
	v_fmamk_f32 v138, v138, 0x3b800000, v229
	v_rsq_f32_e32 v161, v138
	v_mov_b32_e32 v138, v135
	v_mov_b32_e32 v139, v136
	v_mov_b32_e32 v135, v137
	v_pk_add_f32 v[134:135], v[138:139], v[134:135]
	s_nop 0
	v_add_f32_e32 v134, v134, v135
	v_fmamk_f32 v134, v134, 0x3b800000, v229
	v_rsq_f32_e32 v162, v134
	s_waitcnt vmcnt(0)
; __device__ __forceinline__ u32x4 pack8(const f32x4& a, const f32x4& b) { u32x4 w; w.x = cvt_pk_bf16(a[0], a[1]); w.y = cvt_pk_bf16(a[2], a[3]); w.z = cvt_pk_bf16(b[0], b[1]); w.w = cvt_pk_bf16(b[2], b[3]); return w; }
;     __device__ __forceinline__ void operator()(const f32x4 (&acc)[2][2][4][2], const pg8::Unit& u, int wr, int wc, int fr, int fq) const {
;     ...
;                     for (int i = 0; i < 8; ++i) { const f32x4 pp = *(const f32x4*)(ssqkv + (size_t)(c0 + 128 * hf + i) * 4); sc[hf][i] = __builtin_amdgcn_rsqf(((pp[0] + pp[1]) + (pp[2] + pp[3])) * (1.f / 256.f) + EPS); }
; #pragma unroll
;                 for (int ai = 0; ai < 2; ++ai)
; #pragma unroll
;                     for (int m = 0; m < 4; ++m) { bf16_t* d = vt + (size_t)(u.pm * pg8::BM + ai * pg8::HALF + wr * 64 + m * 16 + fr) * MP + c0;
; #pragma unroll
;                         for (int hf = 0; hf < 2; ++hf) { f32x4 x = acc[ai][hf][m][0], y = acc[ai][hf][m][1];
; #pragma unroll
;                             for (int i = 0; i < 4; ++i) { x[i] *= sc[hf][i]; y[i] *= sc[hf][4 + i]; }
;                             *(u32x4*)(d + 128 * hf) = pack8(x, y); }
;                         asm volatile("" ::: "memory"); }
	v_mov_b32_e32 v134, v220
	v_mov_b32_e32 v135, v221
	v_mov_b32_e32 v136, v222
	v_mov_b32_e32 v137, v223
	v_mov_b32_e32 v138, v224
	v_mov_b32_e32 v139, v225
	v_mov_b32_e32 v140, v226
	v_mov_b32_e32 v141, v227
	v_mov_b32_e32 v142, v244
	v_mov_b32_e32 v143, v245
	v_mov_b32_e32 v144, v246
	v_mov_b32_e32 v145, v247
	v_mov_b32_e32 v146, v248
	v_mov_b32_e32 v147, v249
	v_mov_b32_e32 v148, v250
	v_mov_b32_e32 v149, v251
	v_mov_b32_e32 v164, v147
	v_mov_b32_e32 v165, v148
	v_mov_b32_e32 v147, v149
	v_pk_add_f32 v[146:147], v[164:165], v[146:147]
	v_mul_f32_e32 v149, v133, v154
	v_add_f32_e32 v146, v146, v147
	v_fmamk_f32 v146, v146, 0x3b800000, v229
	v_rsq_f32_e32 v148, v146
	v_mov_b32_e32 v146, v143
	v_mov_b32_e32 v147, v144
	v_mov_b32_e32 v143, v145
	v_pk_add_f32 v[142:143], v[146:147], v[142:143]
	v_lshl_add_u32 v145, s63, 8, v17
	v_add_f32_e32 v142, v142, v143
	v_fmamk_f32 v142, v142, 0x3b800000, v229
	v_rsq_f32_e32 v144, v142
	v_mov_b32_e32 v142, v139
	v_mov_b32_e32 v143, v140
	v_mov_b32_e32 v139, v141
	v_pk_add_f32 v[138:139], v[142:143], v[138:139]
	v_mul_f32_e32 v146, v132, v153
	v_add_f32_e32 v138, v138, v139
	v_fmamk_f32 v138, v138, 0x3b800000, v229
	v_rsq_f32_e32 v142, v138
	v_mov_b32_e32 v138, v135
	v_mov_b32_e32 v139, v136
	v_mov_b32_e32 v135, v137
	v_pk_add_f32 v[134:135], v[138:139], v[134:135]
	v_mul_f32_e32 v136, v130, v0
	v_add_f32_e32 v134, v134, v135
	v_fmamk_f32 v134, v134, 0x3b800000, v229
	v_rsq_f32_e32 v143, v134
	v_lshl_add_u64 v[134:135], v[150:151], 1, s[22:23]
	v_mad_i64_i32 v[140:141], s[22:23], v145, s36, v[134:135]
	v_mul_f32_e32 v138, v126, v155
	v_mul_f32_e32 v137, v131, v152
	v_mul_f32_e32 v139, v127, v156
	v_cvt_pk_bf16_f32 v136, v136, v137
	v_mul_f32_e32 v147, v128, v157
	v_mul_f32_e32 v150, v129, v158
	v_cvt_pk_bf16_f32 v137, v146, v149
	v_cvt_pk_bf16_f32 v138, v138, v139
	v_cvt_pk_bf16_f32 v139, v147, v150
	global_store_dwordx4 v[140:141], v[136:139], off
	v_mul_f32_e32 v146, v124, v161
	v_mul_f32_e32 v147, v120, v142
	v_mul_f32_e32 v136, v122, v159
	v_mul_f32_e32 v138, v118, v148
	v_mul_f32_e32 v137, v123, v160
	v_mul_f32_e32 v139, v119, v144
	v_cvt_pk_bf16_f32 v136, v136, v137
	v_mul_f32_e32 v149, v125, v162
	v_mul_f32_e32 v150, v121, v143
	v_cvt_pk_bf16_f32 v137, v146, v149
	v_cvt_pk_bf16_f32 v138, v138, v139
	v_cvt_pk_bf16_f32 v139, v147, v150
	global_store_dwordx4 v[140:141], v[136:139], off offset:256
	v_mul_f32_e32 v146, v116, v153
	v_mul_f32_e32 v147, v112, v157
	v_or_b32_e32 v136, 16, v145
	v_mad_i64_i32 v[140:141], s[22:23], v136, s36, v[134:135]
	v_mul_f32_e32 v136, v114, v0
	v_mul_f32_e32 v138, v110, v155
	v_mul_f32_e32 v137, v115, v152
	v_mul_f32_e32 v139, v111, v156
	v_cvt_pk_bf16_f32 v136, v136, v137
	v_mul_f32_e32 v149, v117, v154
	v_mul_f32_e32 v150, v113, v158
	v_cvt_pk_bf16_f32 v137, v146, v149
	v_cvt_pk_bf16_f32 v138, v138, v139
	v_cvt_pk_bf16_f32 v139, v147, v150
	global_store_dwordx4 v[140:141], v[136:139], off
	v_mul_f32_e32 v146, v108, v161
	v_mul_f32_e32 v147, v104, v142
	v_mul_f32_e32 v136, v106, v159
	v_mul_f32_e32 v138, v102, v148
	v_mul_f32_e32 v137, v107, v160
	v_mul_f32_e32 v139, v103, v144
	v_cvt_pk_bf16_f32 v136, v136, v137
	v_mul_f32_e32 v149, v109, v162
	v_mul_f32_e32 v150, v105, v143
	v_cvt_pk_bf16_f32 v137, v146, v149
	v_cvt_pk_bf16_f32 v138, v138, v139
	v_cvt_pk_bf16_f32 v139, v147, v150
	global_store_dwordx4 v[140:141], v[136:139], off offset:256
	v_mul_f32_e32 v146, v100, v153
	v_mul_f32_e32 v147, v96, v157
	v_or_b32_e32 v136, 32, v145
	v_mad_i64_i32 v[140:141], s[22:23], v136, s36, v[134:135]
	v_mul_f32_e32 v136, v98, v0
	v_mul_f32_e32 v138, v94, v155
	v_mul_f32_e32 v137, v99, v152
	v_mul_f32_e32 v139, v95, v156
	v_cvt_pk_bf16_f32 v136, v136, v137
	v_mul_f32_e32 v149, v101, v154
	v_mul_f32_e32 v150, v97, v158
	v_cvt_pk_bf16_f32 v137, v146, v149
	v_cvt_pk_bf16_f32 v138, v138, v139
	v_cvt_pk_bf16_f32 v139, v147, v150
	global_store_dwordx4 v[140:141], v[136:139], off
	v_mul_f32_e32 v146, v92, v161
	v_mul_f32_e32 v147, v88, v142
	v_mul_f32_e32 v136, v90, v159
	v_mul_f32_e32 v138, v86, v148
	v_mul_f32_e32 v137, v91, v160
	v_mul_f32_e32 v139, v87, v144
	v_cvt_pk_bf16_f32 v136, v136, v137
	v_mul_f32_e32 v149, v93, v162
	v_mul_f32_e32 v150, v89, v143
	v_cvt_pk_bf16_f32 v137, v146, v149
	v_cvt_pk_bf16_f32 v138, v138, v139
	v_cvt_pk_bf16_f32 v139, v147, v150
	global_store_dwordx4 v[140:141], v[136:139], off offset:256
	v_mul_f32_e32 v146, v84, v153
	v_mul_f32_e32 v147, v80, v157
	v_or_b32_e32 v136, 48, v145
	v_mad_i64_i32 v[140:141], s[22:23], v136, s36, v[134:135]
	v_mul_f32_e32 v136, v82, v0
	v_mul_f32_e32 v138, v78, v155
	v_mul_f32_e32 v137, v83, v152
	v_mul_f32_e32 v139, v79, v156
; __device__ __forceinline__ u32x4 pack8(const f32x4& a, const f32x4& b) { u32x4 w; w.x = cvt_pk_bf16(a[0], a[1]); w.y = cvt_pk_bf16(a[2], a[3]); w.z = cvt_pk_bf16(b[0], b[1]); w.w = cvt_pk_bf16(b[2], b[3]); return w; }
;     __device__ __forceinline__ void operator()(const f32x4 (&acc)[2][2][4][2], const pg8::Unit& u, int wr, int wc, int fr, int fq) const {
;     ...
;                 for (int ai = 0; ai < 2; ++ai)
; #pragma unroll
;                     for (int m = 0; m < 4; ++m) { bf16_t* d = vt + (size_t)(u.pm * pg8::BM + ai * pg8::HALF + wr * 64 + m * 16 + fr) * MP + c0;
; #pragma unroll
;                         for (int hf = 0; hf < 2; ++hf) { f32x4 x = acc[ai][hf][m][0], y = acc[ai][hf][m][1];
; #pragma unroll
;                             for (int i = 0; i < 4; ++i) { x[i] *= sc[hf][i]; y[i] *= sc[hf][4 + i]; }
;                             *(u32x4*)(d + 128 * hf) = pack8(x, y); }
;                         asm volatile("" ::: "memory"); }
	v_cvt_pk_bf16_f32 v136, v136, v137
	v_mul_f32_e32 v149, v85, v154
	v_mul_f32_e32 v150, v81, v158
	v_cvt_pk_bf16_f32 v137, v146, v149
	v_cvt_pk_bf16_f32 v138, v138, v139
	v_cvt_pk_bf16_f32 v139, v147, v150
	global_store_dwordx4 v[140:141], v[136:139], off
	v_mul_f32_e32 v146, v76, v161
	v_mul_f32_e32 v147, v72, v142
	v_mul_f32_e32 v136, v74, v159
	v_mul_f32_e32 v138, v70, v148
	v_mul_f32_e32 v137, v75, v160
	v_mul_f32_e32 v139, v71, v144
	v_cvt_pk_bf16_f32 v136, v136, v137
	v_mul_f32_e32 v149, v77, v162
	v_mul_f32_e32 v150, v73, v143
	v_cvt_pk_bf16_f32 v137, v146, v149
	v_cvt_pk_bf16_f32 v138, v138, v139
	v_cvt_pk_bf16_f32 v139, v147, v150
	global_store_dwordx4 v[140:141], v[136:139], off offset:256
	v_mul_f32_e32 v146, v68, v153
	v_mul_f32_e32 v147, v64, v157
	v_add_u32_e32 v136, 0x80, v145
	v_mad_i64_i32 v[140:141], s[22:23], v136, s36, v[134:135]
	v_mul_f32_e32 v136, v66, v0
	v_mul_f32_e32 v138, v62, v155
	v_mul_f32_e32 v137, v67, v152
	v_mul_f32_e32 v139, v63, v156
	v_cvt_pk_bf16_f32 v136, v136, v137
	v_mul_f32_e32 v149, v69, v154
	v_mul_f32_e32 v150, v65, v158
	v_cvt_pk_bf16_f32 v137, v146, v149
	v_cvt_pk_bf16_f32 v138, v138, v139
	v_cvt_pk_bf16_f32 v139, v147, v150
	global_store_dwordx4 v[140:141], v[136:139], off
	v_mul_f32_e32 v146, v60, v161
	v_mul_f32_e32 v147, v56, v142
	v_mul_f32_e32 v136, v58, v159
	v_mul_f32_e32 v138, v54, v148
	v_mul_f32_e32 v137, v59, v160
	v_mul_f32_e32 v139, v55, v144
	v_cvt_pk_bf16_f32 v136, v136, v137
	v_mul_f32_e32 v149, v61, v162
	v_mul_f32_e32 v150, v57, v143
	v_cvt_pk_bf16_f32 v137, v146, v149
	v_cvt_pk_bf16_f32 v138, v138, v139
	v_cvt_pk_bf16_f32 v139, v147, v150
	global_store_dwordx4 v[140:141], v[136:139], off offset:256
	v_mul_f32_e32 v146, v52, v153
	v_mul_f32_e32 v147, v48, v157
	v_add_u32_e32 v136, 0x90, v145
	v_mad_i64_i32 v[140:141], s[22:23], v136, s36, v[134:135]
	v_mul_f32_e32 v136, v50, v0
	v_mul_f32_e32 v138, v46, v155
	v_mul_f32_e32 v137, v51, v152
	v_mul_f32_e32 v139, v47, v156
	v_cvt_pk_bf16_f32 v136, v136, v137
	v_mul_f32_e32 v149, v53, v154
	v_mul_f32_e32 v150, v49, v158
	v_cvt_pk_bf16_f32 v137, v146, v149
	v_cvt_pk_bf16_f32 v138, v138, v139
	v_cvt_pk_bf16_f32 v139, v147, v150
	global_store_dwordx4 v[140:141], v[136:139], off
	v_mul_f32_e32 v146, v44, v161
	v_mul_f32_e32 v147, v40, v142
	v_mul_f32_e32 v136, v42, v159
	v_mul_f32_e32 v138, v38, v148
	v_mul_f32_e32 v137, v43, v160
	v_mul_f32_e32 v139, v39, v144
	v_cvt_pk_bf16_f32 v136, v136, v137
	v_mul_f32_e32 v149, v45, v162
	v_mul_f32_e32 v150, v41, v143
	v_cvt_pk_bf16_f32 v137, v146, v149
	v_cvt_pk_bf16_f32 v138, v138, v139
	v_cvt_pk_bf16_f32 v139, v147, v150
	global_store_dwordx4 v[140:141], v[136:139], off offset:256
	v_mul_f32_e32 v146, v36, v153
	v_mul_f32_e32 v147, v32, v157
	v_add_u32_e32 v136, 0xa0, v145
	v_mad_i64_i32 v[140:141], s[22:23], v136, s36, v[134:135]
	v_mul_f32_e32 v136, v34, v0
	v_mul_f32_e32 v138, v30, v155
	v_mul_f32_e32 v137, v35, v152
	v_mul_f32_e32 v139, v31, v156
	v_cvt_pk_bf16_f32 v136, v136, v137
	v_mul_f32_e32 v149, v37, v154
	v_mul_f32_e32 v150, v33, v158
	v_cvt_pk_bf16_f32 v137, v146, v149
	v_cvt_pk_bf16_f32 v138, v138, v139
	v_cvt_pk_bf16_f32 v139, v147, v150
	global_store_dwordx4 v[140:141], v[136:139], off
	v_mul_f32_e32 v146, v28, v161
	v_mul_f32_e32 v147, v24, v142
	v_mul_f32_e32 v136, v26, v159
	v_mul_f32_e32 v138, v22, v148
	v_mul_f32_e32 v137, v27, v160
	v_mul_f32_e32 v139, v23, v144
	v_cvt_pk_bf16_f32 v136, v136, v137
	v_mul_f32_e32 v149, v29, v162
	v_mul_f32_e32 v150, v25, v143
	v_cvt_pk_bf16_f32 v137, v146, v149
	v_cvt_pk_bf16_f32 v138, v138, v139
	v_cvt_pk_bf16_f32 v139, v147, v150
	global_store_dwordx4 v[140:141], v[136:139], off offset:256
	v_mul_f32_e32 v0, v18, v0
	v_mul_f32_e32 v140, v12, v157
	v_add_u32_e32 v136, 0xb0, v145
	v_mad_i64_i32 v[138:139], s[22:23], v136, s36, v[134:135]
	v_mul_f32_e32 v136, v10, v155
	v_mul_f32_e32 v134, v19, v152
	v_mul_f32_e32 v137, v11, v156
	v_mul_f32_e32 v135, v20, v153
	v_mul_f32_e32 v141, v21, v154
	v_mul_f32_e32 v145, v13, v158
	v_cvt_pk_bf16_f32 v134, v0, v134
	v_cvt_pk_bf16_f32 v135, v135, v141
	v_cvt_pk_bf16_f32 v136, v136, v137
	v_cvt_pk_bf16_f32 v137, v140, v145
	global_store_dwordx4 v[138:139], v[134:137], off
	v_mul_f32_e32 v0, v6, v159
	v_mul_f32_e32 v140, v4, v142
	v_mul_f32_e32 v136, v2, v148
	v_mul_f32_e32 v134, v7, v160
	v_mul_f32_e32 v137, v3, v144
	v_mul_f32_e32 v135, v8, v161
	v_mul_f32_e32 v141, v9, v162
	v_mul_f32_e32 v142, v5, v143
	v_cvt_pk_bf16_f32 v134, v0, v134
	v_cvt_pk_bf16_f32 v135, v135, v141
	v_cvt_pk_bf16_f32 v136, v136, v137
	v_cvt_pk_bf16_f32 v137, v140, v142
	global_store_dwordx4 v[138:139], v[134:137], off offset:256
	s_mov_b64 s[22:23], 0
